# v67 plus one unreachable 4-byte pad after the ConvGate stubs so that all following code keeps its 8-byte instruction phase (code-placement check)
# speedup vs baseline: 1.0100x; 1.0063x over previous
.Lcg_skip3:
	s_waitcnt vmcnt(0)
	s_branch .LBB0_135
	s_nop 0
